# ml_out: row sums and 1/den fused into the S stage (per-lane sums + permlane swaps), serialized 128-thread row-sum stage and one barrier per direction removed
# speedup vs baseline: 1.0707x; 1.0048x over previous
; __device__ __forceinline__ float fexp(float x) { return __expf(x); }
; __device__ __forceinline__ float frcp(float x) { return __builtin_amdgcn_rcpf(x); }
; __device__ void ml_out_tile(unsigned char* lds, const Params& p, int l, int b, int h, int n) {
;     ...
;     {
;       const float rv = ROWV[t];
; #pragma unroll
;       for (int sf = 0; sf < 8; ++sf) {
;         f32x4 acc = (f32x4){0.f, 0.f, 0.f, 0.f};
; #pragma unroll
;         for (int ks = 0; ks < 4; ++ks) {
;           const bf16x8 kf = ldfrag(Ks + (sf * 16 + lr) * 136 + ks * 32 + lg * 8);
;           acc = mfma16(kf, qf[ks], acc);
;         }
;         float pv[4];
; #pragma unroll
;         for (int j = 0; j < 4; ++j) {
;           const int s = sf * 16 + lg * 4 + j;
;           const bool ok = (dir == 0) ? (s <= t) : (s >= t);
;           pv[j] = ok ? acc[j] * fexp(rv + COLV[s]) : 0.f;
;         }
;         uint2 u; u.x = pack2(pv[0], pv[1]); u.y = pack2(pv[2], pv[3]);
;         *(uint2*)(Ps + t * 136 + sf * 16 + lg * 4) = u;
;       }
;     }
;     ...
;     if (tid < 128) {
;       float rs = 0.f;
; #pragma unroll
;       for (int c8 = 0; c8 < 16; ++c8) {
;         float f[8];
;         unpack8(*(const uint4*)(Ps + tid * 136 + c8 * 8), f);
; #pragma unroll
;         for (int e = 0; e < 8; ++e) rs += f[e];
;       }
;       const float den = rs + WI[tid] * QN[tid];
;       DINV[tid] = frcp(fmaxf(fabsf(den), EM[tid]));
;     }
.LBB0_742:
	s_lshl_b32 s76, s33, 11
	s_add_i32 s76, s76, 0x22000
	s_lshl_b32 s77, s33, 9
	s_add_i32 s77, s77, 0x24200
	s_lshl_b32 s10, s33, 1
	s_sub_i32 s10, 1, s10
	s_lshl_b32 s11, s10, 1
	s_mul_i32 s12, s10, 3
	s_lshl_b32 s13, s10, 4
	v_lshl_add_u32 v100, v240, 2, s76
	v_lshl_add_u32 v217, v240, 2, s77
	v_lshl_add_u32 v37, v68, 2, s76
	v_add_u32_e32 v38, v110, v200
	v_sub_u32_e32 v39, v240, v68
	v_mul_lo_u32 v39, v39, s10
	ds_read2st64_b32 v[214:215], v100 offset0:16 offset1:18
	ds_read_b32 v216, v217
	v_mov_b32_e32 v210, 0
	v_mov_b32_e32 v211, 0
	ds_read_b128 v[158:161], v124 offset:34816
	ds_read_b128 v[162:165], v124 offset:34880
	ds_read_b128 v[166:169], v124 offset:34944
	ds_read_b128 v[170:173], v124 offset:35008
	ds_read_b32 v36, v100 offset:3072
	ds_read_b128 v[126:129], v37 offset:3584
	ds_read_b128 v[130:133], v37 offset:3648
	ds_read_b128 v[134:137], v37 offset:3712
	ds_read_b128 v[138:141], v37 offset:3776
	ds_read_b128 v[174:177], v124 offset:39168
	ds_read_b128 v[178:181], v124 offset:39232
	ds_read_b128 v[182:185], v124 offset:39296
	ds_read_b128 v[186:189], v124 offset:39360
	s_waitcnt lgkmcnt(9)
	v_mfma_f32_16x16x32_bf16 v[32:35], v[158:161], v[0:3], 0
	v_mfma_f32_16x16x32_bf16 v[32:35], v[162:165], v[4:7], v[32:35]
	v_mfma_f32_16x16x32_bf16 v[32:35], v[166:169], v[8:11], v[32:35]
	v_mfma_f32_16x16x32_bf16 v[32:35], v[170:173], v[12:15], v[32:35]
	ds_read_b128 v[142:145], v37 offset:3840
	ds_read_b128 v[146:149], v37 offset:3904
	ds_read_b128 v[150:153], v37 offset:3968
	ds_read_b128 v[154:157], v37 offset:4032
	s_waitcnt lgkmcnt(8)
	v_add_f32_e32 v102, v36, v126
	v_add_f32_e32 v103, v36, v127
	v_add_f32_e32 v104, v36, v128
	v_add_f32_e32 v105, v36, v129
	v_mul_f32_e32 v102, 0x3fb8aa3b, v102
	v_mul_f32_e32 v103, 0x3fb8aa3b, v103
	v_mul_f32_e32 v104, 0x3fb8aa3b, v104
	v_mul_f32_e32 v105, 0x3fb8aa3b, v105
	v_exp_f32_e32 v102, v102
	v_exp_f32_e32 v103, v103
	v_exp_f32_e32 v104, v104
	v_exp_f32_e32 v105, v105
	v_cmp_le_i32_e64 s[2:3], 0, v39
	v_cmp_le_i32_e64 s[4:5], s10, v39
	v_cmp_le_i32_e64 s[6:7], s11, v39
	v_cmp_le_i32_e64 s[8:9], s12, v39
	v_mul_f32_e32 v32, v32, v102
	v_mul_f32_e32 v33, v33, v103
	v_mul_f32_e32 v34, v34, v104
	v_mul_f32_e32 v35, v35, v105
	v_cndmask_b32_e64 v32, 0, v32, s[2:3]
	v_cndmask_b32_e64 v33, 0, v33, s[4:5]
	v_cndmask_b32_e64 v34, 0, v34, s[6:7]
	v_cndmask_b32_e64 v35, 0, v35, s[8:9]
	v_subrev_u32_e32 v39, s13, v39
	v_cvt_pk_bf16_f32 v102, v32, v33
	v_cvt_pk_bf16_f32 v103, v34, v35
	ds_write_b64 v38, v[102:103]
	v_lshlrev_b32_e32 v212, 16, v102
	v_and_b32_e32 v213, 0xffff0000, v102
	v_pk_add_f32 v[210:211], v[210:211], v[212:213]
	v_lshlrev_b32_e32 v212, 16, v103
	v_and_b32_e32 v213, 0xffff0000, v103
	v_pk_add_f32 v[210:211], v[210:211], v[212:213]
	ds_read_b128 v[158:161], v124 offset:43520
	ds_read_b128 v[162:165], v124 offset:43584
	ds_read_b128 v[166:169], v124 offset:43648
	ds_read_b128 v[170:173], v124 offset:43712
	s_waitcnt lgkmcnt(9)
	v_mfma_f32_16x16x32_bf16 v[32:35], v[174:177], v[0:3], 0
	v_mfma_f32_16x16x32_bf16 v[32:35], v[178:181], v[4:7], v[32:35]
	v_mfma_f32_16x16x32_bf16 v[32:35], v[182:185], v[8:11], v[32:35]
	v_mfma_f32_16x16x32_bf16 v[32:35], v[186:189], v[12:15], v[32:35]
	v_add_f32_e32 v102, v36, v130
	v_add_f32_e32 v103, v36, v131
	v_add_f32_e32 v104, v36, v132
	v_add_f32_e32 v105, v36, v133
	v_mul_f32_e32 v102, 0x3fb8aa3b, v102
	v_mul_f32_e32 v103, 0x3fb8aa3b, v103
	v_mul_f32_e32 v104, 0x3fb8aa3b, v104
	v_mul_f32_e32 v105, 0x3fb8aa3b, v105
	v_exp_f32_e32 v102, v102
	v_exp_f32_e32 v103, v103
	v_exp_f32_e32 v104, v104
	v_exp_f32_e32 v105, v105
	v_cmp_le_i32_e64 s[2:3], 0, v39
	v_cmp_le_i32_e64 s[4:5], s10, v39
	v_cmp_le_i32_e64 s[6:7], s11, v39
	v_cmp_le_i32_e64 s[8:9], s12, v39
	v_mul_f32_e32 v32, v32, v102
	v_mul_f32_e32 v33, v33, v103
	v_mul_f32_e32 v34, v34, v104
	v_mul_f32_e32 v35, v35, v105
	v_cndmask_b32_e64 v32, 0, v32, s[2:3]
	v_cndmask_b32_e64 v33, 0, v33, s[4:5]
	v_cndmask_b32_e64 v34, 0, v34, s[6:7]
	v_cndmask_b32_e64 v35, 0, v35, s[8:9]
	v_subrev_u32_e32 v39, s13, v39
	v_cvt_pk_bf16_f32 v102, v32, v33
	v_cvt_pk_bf16_f32 v103, v34, v35
	ds_write_b64 v38, v[102:103] offset:32
	v_lshlrev_b32_e32 v212, 16, v102
	v_and_b32_e32 v213, 0xffff0000, v102
	v_pk_add_f32 v[210:211], v[210:211], v[212:213]
	v_lshlrev_b32_e32 v212, 16, v103
	v_and_b32_e32 v213, 0xffff0000, v103
	v_pk_add_f32 v[210:211], v[210:211], v[212:213]
	ds_read_b128 v[174:177], v124 offset:47872
	ds_read_b128 v[178:181], v124 offset:47936
	ds_read_b128 v[182:185], v124 offset:48000
	ds_read_b128 v[186:189], v124 offset:48064
	s_waitcnt lgkmcnt(5)
	v_mfma_f32_16x16x32_bf16 v[32:35], v[158:161], v[0:3], 0
	v_mfma_f32_16x16x32_bf16 v[32:35], v[162:165], v[4:7], v[32:35]
	v_mfma_f32_16x16x32_bf16 v[32:35], v[166:169], v[8:11], v[32:35]
	v_mfma_f32_16x16x32_bf16 v[32:35], v[170:173], v[12:15], v[32:35]
	v_add_f32_e32 v102, v36, v134
	v_add_f32_e32 v103, v36, v135
	v_add_f32_e32 v104, v36, v136
	v_add_f32_e32 v105, v36, v137
	v_mul_f32_e32 v102, 0x3fb8aa3b, v102
	v_mul_f32_e32 v103, 0x3fb8aa3b, v103
	v_mul_f32_e32 v104, 0x3fb8aa3b, v104
	v_mul_f32_e32 v105, 0x3fb8aa3b, v105
	v_exp_f32_e32 v102, v102
	v_exp_f32_e32 v103, v103
	v_exp_f32_e32 v104, v104
	v_exp_f32_e32 v105, v105
	v_cmp_le_i32_e64 s[2:3], 0, v39
	v_cmp_le_i32_e64 s[4:5], s10, v39
	v_cmp_le_i32_e64 s[6:7], s11, v39
	v_cmp_le_i32_e64 s[8:9], s12, v39
	v_mul_f32_e32 v32, v32, v102
	v_mul_f32_e32 v33, v33, v103
	v_mul_f32_e32 v34, v34, v104
	v_mul_f32_e32 v35, v35, v105
	v_cndmask_b32_e64 v32, 0, v32, s[2:3]
	v_cndmask_b32_e64 v33, 0, v33, s[4:5]
	v_cndmask_b32_e64 v34, 0, v34, s[6:7]
	v_cndmask_b32_e64 v35, 0, v35, s[8:9]
	v_subrev_u32_e32 v39, s13, v39
	v_cvt_pk_bf16_f32 v102, v32, v33
	v_cvt_pk_bf16_f32 v103, v34, v35
	ds_write_b64 v38, v[102:103] offset:64
	v_lshlrev_b32_e32 v212, 16, v102
	v_and_b32_e32 v213, 0xffff0000, v102
	v_pk_add_f32 v[210:211], v[210:211], v[212:213]
	v_lshlrev_b32_e32 v212, 16, v103
	v_and_b32_e32 v213, 0xffff0000, v103
	v_pk_add_f32 v[210:211], v[210:211], v[212:213]
	ds_read_b128 v[158:161], v124 offset:52224
	ds_read_b128 v[162:165], v124 offset:52288
	ds_read_b128 v[166:169], v124 offset:52352
	ds_read_b128 v[170:173], v124 offset:52416
	s_waitcnt lgkmcnt(5)
; __device__ __forceinline__ float fexp(float x) { return __expf(x); }
; __device__ void ml_out_tile(unsigned char* lds, const Params& p, int l, int b, int h, int n) {
;     ...
;       for (int sf = 0; sf < 8; ++sf) {
;         f32x4 acc = (f32x4){0.f, 0.f, 0.f, 0.f};
; #pragma unroll
;         for (int ks = 0; ks < 4; ++ks) {
;           const bf16x8 kf = ldfrag(Ks + (sf * 16 + lr) * 136 + ks * 32 + lg * 8);
;           acc = mfma16(kf, qf[ks], acc);
;         }
;         float pv[4];
; #pragma unroll
;         for (int j = 0; j < 4; ++j) {
;           const int s = sf * 16 + lg * 4 + j;
;           const bool ok = (dir == 0) ? (s <= t) : (s >= t);
;           pv[j] = ok ? acc[j] * fexp(rv + COLV[s]) : 0.f;
;         }
;         uint2 u; u.x = pack2(pv[0], pv[1]); u.y = pack2(pv[2], pv[3]);
;         *(uint2*)(Ps + t * 136 + sf * 16 + lg * 4) = u;
;       }
	v_mfma_f32_16x16x32_bf16 v[32:35], v[174:177], v[0:3], 0
	v_mfma_f32_16x16x32_bf16 v[32:35], v[178:181], v[4:7], v[32:35]
	v_mfma_f32_16x16x32_bf16 v[32:35], v[182:185], v[8:11], v[32:35]
	v_mfma_f32_16x16x32_bf16 v[32:35], v[186:189], v[12:15], v[32:35]
	v_add_f32_e32 v102, v36, v138
	v_add_f32_e32 v103, v36, v139
	v_add_f32_e32 v104, v36, v140
	v_add_f32_e32 v105, v36, v141
	v_mul_f32_e32 v102, 0x3fb8aa3b, v102
	v_mul_f32_e32 v103, 0x3fb8aa3b, v103
	v_mul_f32_e32 v104, 0x3fb8aa3b, v104
	v_mul_f32_e32 v105, 0x3fb8aa3b, v105
	v_exp_f32_e32 v102, v102
	v_exp_f32_e32 v103, v103
	v_exp_f32_e32 v104, v104
	v_exp_f32_e32 v105, v105
	v_cmp_le_i32_e64 s[2:3], 0, v39
	v_cmp_le_i32_e64 s[4:5], s10, v39
	v_cmp_le_i32_e64 s[6:7], s11, v39
	v_cmp_le_i32_e64 s[8:9], s12, v39
	v_mul_f32_e32 v32, v32, v102
	v_mul_f32_e32 v33, v33, v103
	v_mul_f32_e32 v34, v34, v104
	v_mul_f32_e32 v35, v35, v105
	v_cndmask_b32_e64 v32, 0, v32, s[2:3]
	v_cndmask_b32_e64 v33, 0, v33, s[4:5]
	v_cndmask_b32_e64 v34, 0, v34, s[6:7]
	v_cndmask_b32_e64 v35, 0, v35, s[8:9]
	v_subrev_u32_e32 v39, s13, v39
	v_cvt_pk_bf16_f32 v102, v32, v33
	v_cvt_pk_bf16_f32 v103, v34, v35
	ds_write_b64 v38, v[102:103] offset:96
	v_lshlrev_b32_e32 v212, 16, v102
	v_and_b32_e32 v213, 0xffff0000, v102
	v_pk_add_f32 v[210:211], v[210:211], v[212:213]
	v_lshlrev_b32_e32 v212, 16, v103
	v_and_b32_e32 v213, 0xffff0000, v103
	v_pk_add_f32 v[210:211], v[210:211], v[212:213]
	ds_read_b128 v[174:177], v124 offset:56576
	ds_read_b128 v[178:181], v124 offset:56640
	ds_read_b128 v[182:185], v124 offset:56704
	ds_read_b128 v[186:189], v124 offset:56768
	s_waitcnt lgkmcnt(5)
	v_mfma_f32_16x16x32_bf16 v[32:35], v[158:161], v[0:3], 0
	v_mfma_f32_16x16x32_bf16 v[32:35], v[162:165], v[4:7], v[32:35]
	v_mfma_f32_16x16x32_bf16 v[32:35], v[166:169], v[8:11], v[32:35]
	v_mfma_f32_16x16x32_bf16 v[32:35], v[170:173], v[12:15], v[32:35]
	v_add_f32_e32 v102, v36, v142
	v_add_f32_e32 v103, v36, v143
	v_add_f32_e32 v104, v36, v144
	v_add_f32_e32 v105, v36, v145
	v_mul_f32_e32 v102, 0x3fb8aa3b, v102
	v_mul_f32_e32 v103, 0x3fb8aa3b, v103
	v_mul_f32_e32 v104, 0x3fb8aa3b, v104
	v_mul_f32_e32 v105, 0x3fb8aa3b, v105
	v_exp_f32_e32 v102, v102
	v_exp_f32_e32 v103, v103
	v_exp_f32_e32 v104, v104
	v_exp_f32_e32 v105, v105
	v_cmp_le_i32_e64 s[2:3], 0, v39
	v_cmp_le_i32_e64 s[4:5], s10, v39
	v_cmp_le_i32_e64 s[6:7], s11, v39
	v_cmp_le_i32_e64 s[8:9], s12, v39
	v_mul_f32_e32 v32, v32, v102
	v_mul_f32_e32 v33, v33, v103
	v_mul_f32_e32 v34, v34, v104
	v_mul_f32_e32 v35, v35, v105
	v_cndmask_b32_e64 v32, 0, v32, s[2:3]
	v_cndmask_b32_e64 v33, 0, v33, s[4:5]
	v_cndmask_b32_e64 v34, 0, v34, s[6:7]
	v_cndmask_b32_e64 v35, 0, v35, s[8:9]
	v_subrev_u32_e32 v39, s13, v39
	v_cvt_pk_bf16_f32 v102, v32, v33
	v_cvt_pk_bf16_f32 v103, v34, v35
	ds_write_b64 v38, v[102:103] offset:128
	v_lshlrev_b32_e32 v212, 16, v102
	v_and_b32_e32 v213, 0xffff0000, v102
	v_pk_add_f32 v[210:211], v[210:211], v[212:213]
	v_lshlrev_b32_e32 v212, 16, v103
	v_and_b32_e32 v213, 0xffff0000, v103
	v_pk_add_f32 v[210:211], v[210:211], v[212:213]
	ds_read_b128 v[158:161], v124 offset:60928
	ds_read_b128 v[162:165], v124 offset:60992
	ds_read_b128 v[166:169], v124 offset:61056
	ds_read_b128 v[170:173], v124 offset:61120
	s_waitcnt lgkmcnt(5)
	v_mfma_f32_16x16x32_bf16 v[32:35], v[174:177], v[0:3], 0
	v_mfma_f32_16x16x32_bf16 v[32:35], v[178:181], v[4:7], v[32:35]
	v_mfma_f32_16x16x32_bf16 v[32:35], v[182:185], v[8:11], v[32:35]
	v_mfma_f32_16x16x32_bf16 v[32:35], v[186:189], v[12:15], v[32:35]
	v_add_f32_e32 v102, v36, v146
	v_add_f32_e32 v103, v36, v147
	v_add_f32_e32 v104, v36, v148
	v_add_f32_e32 v105, v36, v149
	v_mul_f32_e32 v102, 0x3fb8aa3b, v102
	v_mul_f32_e32 v103, 0x3fb8aa3b, v103
	v_mul_f32_e32 v104, 0x3fb8aa3b, v104
	v_mul_f32_e32 v105, 0x3fb8aa3b, v105
	v_exp_f32_e32 v102, v102
	v_exp_f32_e32 v103, v103
	v_exp_f32_e32 v104, v104
	v_exp_f32_e32 v105, v105
	v_cmp_le_i32_e64 s[2:3], 0, v39
	v_cmp_le_i32_e64 s[4:5], s10, v39
	v_cmp_le_i32_e64 s[6:7], s11, v39
	v_cmp_le_i32_e64 s[8:9], s12, v39
	v_mul_f32_e32 v32, v32, v102
	v_mul_f32_e32 v33, v33, v103
	v_mul_f32_e32 v34, v34, v104
	v_mul_f32_e32 v35, v35, v105
	v_cndmask_b32_e64 v32, 0, v32, s[2:3]
	v_cndmask_b32_e64 v33, 0, v33, s[4:5]
	v_cndmask_b32_e64 v34, 0, v34, s[6:7]
	v_cndmask_b32_e64 v35, 0, v35, s[8:9]
	v_subrev_u32_e32 v39, s13, v39
	v_cvt_pk_bf16_f32 v102, v32, v33
	v_cvt_pk_bf16_f32 v103, v34, v35
	ds_write_b64 v38, v[102:103] offset:160
	v_lshlrev_b32_e32 v212, 16, v102
	v_and_b32_e32 v213, 0xffff0000, v102
	v_pk_add_f32 v[210:211], v[210:211], v[212:213]
	v_lshlrev_b32_e32 v212, 16, v103
	v_and_b32_e32 v213, 0xffff0000, v103
	v_pk_add_f32 v[210:211], v[210:211], v[212:213]
	ds_read_b128 v[174:177], v124 offset:65280
	ds_read_b128 v[178:181], v124 offset:65344
	ds_read_b128 v[182:185], v124 offset:65408
	ds_read_b128 v[186:189], v124 offset:65472
	s_waitcnt lgkmcnt(5)
	v_mfma_f32_16x16x32_bf16 v[32:35], v[158:161], v[0:3], 0
	v_mfma_f32_16x16x32_bf16 v[32:35], v[162:165], v[4:7], v[32:35]
	v_mfma_f32_16x16x32_bf16 v[32:35], v[166:169], v[8:11], v[32:35]
	v_mfma_f32_16x16x32_bf16 v[32:35], v[170:173], v[12:15], v[32:35]
	v_add_f32_e32 v102, v36, v150
	v_add_f32_e32 v103, v36, v151
	v_add_f32_e32 v104, v36, v152
	v_add_f32_e32 v105, v36, v153
	v_mul_f32_e32 v102, 0x3fb8aa3b, v102
	v_mul_f32_e32 v103, 0x3fb8aa3b, v103
	v_mul_f32_e32 v104, 0x3fb8aa3b, v104
	v_mul_f32_e32 v105, 0x3fb8aa3b, v105
	v_exp_f32_e32 v102, v102
	v_exp_f32_e32 v103, v103
	v_exp_f32_e32 v104, v104
	v_exp_f32_e32 v105, v105
	v_cmp_le_i32_e64 s[2:3], 0, v39
	v_cmp_le_i32_e64 s[4:5], s10, v39
	v_cmp_le_i32_e64 s[6:7], s11, v39
	v_cmp_le_i32_e64 s[8:9], s12, v39
	v_mul_f32_e32 v32, v32, v102
	v_mul_f32_e32 v33, v33, v103
	v_mul_f32_e32 v34, v34, v104
	v_mul_f32_e32 v35, v35, v105
	v_cndmask_b32_e64 v32, 0, v32, s[2:3]
	v_cndmask_b32_e64 v33, 0, v33, s[4:5]
	v_cndmask_b32_e64 v34, 0, v34, s[6:7]
	v_cndmask_b32_e64 v35, 0, v35, s[8:9]
	v_subrev_u32_e32 v39, s13, v39
	v_cvt_pk_bf16_f32 v102, v32, v33
	v_cvt_pk_bf16_f32 v103, v34, v35
	ds_write_b64 v38, v[102:103] offset:192
	v_lshlrev_b32_e32 v212, 16, v102
	v_and_b32_e32 v213, 0xffff0000, v102
	v_pk_add_f32 v[210:211], v[210:211], v[212:213]
	v_lshlrev_b32_e32 v212, 16, v103
	v_and_b32_e32 v213, 0xffff0000, v103
	v_pk_add_f32 v[210:211], v[210:211], v[212:213]
	s_waitcnt lgkmcnt(1)
; __device__ __forceinline__ float frcp(float x) { return __builtin_amdgcn_rcpf(x); }
; __device__ void ml_out_tile(unsigned char* lds, const Params& p, int l, int b, int h, int n) {
;     ...
;     __syncthreads();
;     if (tid < 128) {
;       float rs = 0.f;
; #pragma unroll
;       for (int c8 = 0; c8 < 16; ++c8) {
;         float f[8];
;         unpack8(*(const uint4*)(Ps + tid * 136 + c8 * 8), f);
; #pragma unroll
;         for (int e = 0; e < 8; ++e) rs += f[e];
;       }
;       const float den = rs + WI[tid] * QN[tid];
;       DINV[tid] = frcp(fmaxf(fabsf(den), EM[tid]));
;     }
;     __syncthreads();
;     {
;       bf16x8 pf[4];
; #pragma unroll
;       for (int ks = 0; ks < 4; ++ks) pf[ks] = ldfrag(Ps + t * 136 + ks * 32 + lg * 8);
;       const float wi = WI[t];
;       const float di = DINV[t];
; #pragma unroll
;       for (int df = 0; df < 8; ++df) {
;         f32x4 a1 = (f32x4){0.f, 0.f, 0.f, 0.f}, a2 = (f32x4){0.f, 0.f, 0.f, 0.f};
; #pragma unroll
;         for (int ks = 0; ks < 4; ++ks) {
;           const bf16x8 vf = ldfrag(VT + (df * 16 + lr) * 136 + ks * 32 + lg * 8);
;           a1 = mfma16(vf, pf[ks], a1);
;           const bf16x8 cf = ldfrag(C0s + (df * 16 + lr) * 136 + ks * 32 + lg * 8);
;           a2 = mfma16(cf, qf[ks], a2);
;         }
; #pragma unroll
;         for (int j = 0; j < 4; ++j) hsum[df][j] += (a1[j] + wi * a2[j]) * di;
	v_mfma_f32_16x16x32_bf16 v[32:35], v[174:177], v[0:3], 0
	v_mfma_f32_16x16x32_bf16 v[32:35], v[178:181], v[4:7], v[32:35]
	v_mfma_f32_16x16x32_bf16 v[32:35], v[182:185], v[8:11], v[32:35]
	v_mfma_f32_16x16x32_bf16 v[32:35], v[186:189], v[12:15], v[32:35]
	v_add_f32_e32 v102, v36, v154
	v_add_f32_e32 v103, v36, v155
	v_add_f32_e32 v104, v36, v156
	v_add_f32_e32 v105, v36, v157
	v_mul_f32_e32 v102, 0x3fb8aa3b, v102
	v_mul_f32_e32 v103, 0x3fb8aa3b, v103
	v_mul_f32_e32 v104, 0x3fb8aa3b, v104
	v_mul_f32_e32 v105, 0x3fb8aa3b, v105
	v_exp_f32_e32 v102, v102
	v_exp_f32_e32 v103, v103
	v_exp_f32_e32 v104, v104
	v_exp_f32_e32 v105, v105
	v_cmp_le_i32_e64 s[2:3], 0, v39
	v_cmp_le_i32_e64 s[4:5], s10, v39
	v_cmp_le_i32_e64 s[6:7], s11, v39
	v_cmp_le_i32_e64 s[8:9], s12, v39
	v_mul_f32_e32 v32, v32, v102
	v_mul_f32_e32 v33, v33, v103
	v_mul_f32_e32 v34, v34, v104
	v_mul_f32_e32 v35, v35, v105
	v_cndmask_b32_e64 v32, 0, v32, s[2:3]
	v_cndmask_b32_e64 v33, 0, v33, s[4:5]
	v_cndmask_b32_e64 v34, 0, v34, s[6:7]
	v_cndmask_b32_e64 v35, 0, v35, s[8:9]
	v_cvt_pk_bf16_f32 v102, v32, v33
	v_cvt_pk_bf16_f32 v103, v34, v35
	ds_write_b64 v38, v[102:103] offset:224
	v_lshlrev_b32_e32 v212, 16, v102
	v_and_b32_e32 v213, 0xffff0000, v102
	v_pk_add_f32 v[210:211], v[210:211], v[212:213]
	v_lshlrev_b32_e32 v212, 16, v103
	v_and_b32_e32 v213, 0xffff0000, v103
	v_pk_add_f32 v[210:211], v[210:211], v[212:213]
	v_add_f32_e32 v218, v210, v211
	v_max_f32_e32 v212, v215, v215
	v_mov_b32_e32 v219, v218
	s_nop 1
	v_permlane16_swap_b32_e32 v218, v219
	s_nop 1
	v_add_f32_e32 v218, v218, v219
	v_mov_b32_e32 v219, v218
	s_nop 1
	v_permlane32_swap_b32_e32 v218, v219
	s_nop 1
	v_add_f32_e32 v218, v218, v219
	v_fmac_f32_e32 v218, v214, v216
	v_max_f32_e64 v218, |v218|, v212
	v_rcp_f32_e32 v218, v218
	s_nop 0
	ds_write_b32 v111, v218
	s_waitcnt lgkmcnt(0)
	s_barrier
	ds_read_b128 v[36:39], v114
	v_add_u32_e32 v101, v110, v109
	ds_read_b128 v[32:35], v101
	ds_read_b32 v190, v111
	ds_read_b128 v[102:105], v101 offset:64
	ds_read_b128 v[126:129], v115
	ds_read_b128 v[130:133], v114 offset:192
	ds_read_b128 v[134:137], v114 offset:64
	ds_read_b128 v[138:141], v114 offset:128
	s_waitcnt lgkmcnt(3)
	v_mfma_f32_16x16x32_bf16 v[126:129], v[126:129], v[0:3], 0
	s_andn2_b64 vcc, exec, s[72:73]
	s_mov_b64 s[70:71], -1
	v_mfma_f32_16x16x32_bf16 v[36:39], v[36:39], v[32:35], 0
	s_waitcnt lgkmcnt(1)
	v_mfma_f32_16x16x32_bf16 v[36:39], v[134:137], v[102:105], v[36:39]
	ds_read_b128 v[134:137], v115 offset:64
	ds_read_b128 v[142:145], v115 offset:128
	s_waitcnt lgkmcnt(1)
	v_mfma_f32_16x16x32_bf16 v[126:129], v[134:137], v[4:7], v[126:129]
	ds_read_b128 v[134:137], v101 offset:128
	ds_read_b128 v[146:149], v101 offset:192
	s_waitcnt lgkmcnt(1)
	v_mfma_f32_16x16x32_bf16 v[36:39], v[138:141], v[134:137], v[36:39]
	v_mfma_f32_16x16x32_bf16 v[126:129], v[142:145], v[8:11], v[126:129]
	s_waitcnt lgkmcnt(0)
	v_mfma_f32_16x16x32_bf16 v[36:39], v[130:133], v[146:149], v[36:39]
	ds_read_b128 v[130:133], v115 offset:192
	ds_read_b128 v[138:141], v115 offset:4352
	s_waitcnt lgkmcnt(1)
	v_mfma_f32_16x16x32_bf16 v[126:129], v[130:133], v[12:15], v[126:129]
	ds_read_b128 v[130:133], v116
	ds_read_b128 v[142:145], v115 offset:30656
	ds_read_b128 v[150:153], v116 offset:64
	ds_read_b128 v[154:157], v116 offset:128
	s_waitcnt lgkmcnt(3)
	v_mfma_f32_16x16x32_bf16 v[130:133], v[130:133], v[32:35], 0
	v_mfma_f32_16x16x32_bf16 v[138:141], v[138:141], v[0:3], 0
	s_waitcnt lgkmcnt(1)
	v_mfma_f32_16x16x32_bf16 v[130:133], v[150:153], v[102:105], v[130:133]
	ds_read_b128 v[150:153], v115 offset:4416
	ds_read_b128 v[158:161], v115 offset:4480
	s_waitcnt lgkmcnt(1)
	v_mfma_f32_16x16x32_bf16 v[138:141], v[150:153], v[4:7], v[138:141]
	v_mfma_f32_16x16x32_bf16 v[130:133], v[154:157], v[134:137], v[130:133]
	ds_read_b128 v[150:153], v116 offset:192
	ds_read_b128 v[154:157], v117
	s_waitcnt lgkmcnt(2)
	v_mfma_f32_16x16x32_bf16 v[138:141], v[158:161], v[8:11], v[138:141]
	s_waitcnt lgkmcnt(1)
	v_mfma_f32_16x16x32_bf16 v[130:133], v[150:153], v[146:149], v[130:133]
	ds_read_b128 v[150:153], v115 offset:4544
	ds_read_b128 v[158:161], v115 offset:8704
	s_waitcnt lgkmcnt(1)
	v_mfma_f32_16x16x32_bf16 v[138:141], v[150:153], v[12:15], v[138:141]
	v_mfma_f32_16x16x32_bf16 v[150:153], v[154:157], v[32:35], 0
	s_waitcnt lgkmcnt(0)
	v_mfma_f32_16x16x32_bf16 v[154:157], v[158:161], v[0:3], 0
	ds_read_b128 v[158:161], v117 offset:64
	ds_read_b128 v[162:165], v117 offset:128
	s_waitcnt lgkmcnt(1)
	v_mfma_f32_16x16x32_bf16 v[150:153], v[158:161], v[102:105], v[150:153]
	ds_read_b128 v[158:161], v115 offset:8768
	ds_read_b128 v[166:169], v115 offset:8832
	s_waitcnt lgkmcnt(1)
	v_mfma_f32_16x16x32_bf16 v[154:157], v[158:161], v[4:7], v[154:157]
	v_mfma_f32_16x16x32_bf16 v[150:153], v[162:165], v[134:137], v[150:153]
	ds_read_b128 v[158:161], v117 offset:192
	ds_read_b128 v[162:165], v118
	s_waitcnt lgkmcnt(2)
	v_mfma_f32_16x16x32_bf16 v[154:157], v[166:169], v[8:11], v[154:157]
	s_waitcnt lgkmcnt(1)
	v_mfma_f32_16x16x32_bf16 v[150:153], v[158:161], v[146:149], v[150:153]
	ds_read_b128 v[158:161], v115 offset:8896
	ds_read_b128 v[166:169], v115 offset:13056
	s_waitcnt lgkmcnt(1)
	v_mfma_f32_16x16x32_bf16 v[154:157], v[158:161], v[12:15], v[154:157]
	v_mfma_f32_16x16x32_bf16 v[158:161], v[162:165], v[32:35], 0
	s_waitcnt lgkmcnt(0)
	v_mfma_f32_16x16x32_bf16 v[162:165], v[166:169], v[0:3], 0
	ds_read_b128 v[166:169], v118 offset:64
	ds_read_b128 v[170:173], v118 offset:128
	s_waitcnt lgkmcnt(1)
	v_mfma_f32_16x16x32_bf16 v[158:161], v[166:169], v[102:105], v[158:161]
	ds_read_b128 v[166:169], v115 offset:13120
	ds_read_b128 v[174:177], v115 offset:13184
	s_waitcnt lgkmcnt(1)
; __device__ void ml_out_tile(unsigned char* lds, const Params& p, int l, int b, int h, int n) {
;     ...
;     {
;       bf16x8 pf[4];
; #pragma unroll
;       for (int ks = 0; ks < 4; ++ks) pf[ks] = ldfrag(Ps + t * 136 + ks * 32 + lg * 8);
;       const float wi = WI[t];
;       const float di = DINV[t];
; #pragma unroll
;       for (int df = 0; df < 8; ++df) {
;         f32x4 a1 = (f32x4){0.f, 0.f, 0.f, 0.f}, a2 = (f32x4){0.f, 0.f, 0.f, 0.f};
; #pragma unroll
;         for (int ks = 0; ks < 4; ++ks) {
;           const bf16x8 vf = ldfrag(VT + (df * 16 + lr) * 136 + ks * 32 + lg * 8);
;           a1 = mfma16(vf, pf[ks], a1);
;           const bf16x8 cf = ldfrag(C0s + (df * 16 + lr) * 136 + ks * 32 + lg * 8);
;           a2 = mfma16(cf, qf[ks], a2);
;         }
; #pragma unroll
;         for (int j = 0; j < 4; ++j) hsum[df][j] += (a1[j] + wi * a2[j]) * di;
;       }
;     }
;     __syncthreads();
;     if (dir == 0) {
; #pragma unroll
;       for (int i = 0; i < 4; ++i) {
;         const int id = tid + 512 * i;
;         *(uint4*)(C0s + (id >> 4) * 136 + (id & 15) * 8) = cn[i];
;       }
;     }
	v_mfma_f32_16x16x32_bf16 v[162:165], v[166:169], v[4:7], v[162:165]
	v_mfma_f32_16x16x32_bf16 v[158:161], v[170:173], v[134:137], v[158:161]
	ds_read_b128 v[166:169], v118 offset:192
	ds_read_b128 v[170:173], v119
	s_waitcnt lgkmcnt(2)
	v_mfma_f32_16x16x32_bf16 v[162:165], v[174:177], v[8:11], v[162:165]
	s_waitcnt lgkmcnt(1)
	v_mfma_f32_16x16x32_bf16 v[158:161], v[166:169], v[146:149], v[158:161]
	ds_read_b128 v[166:169], v115 offset:13248
	ds_read_b128 v[174:177], v115 offset:17408
	s_waitcnt lgkmcnt(1)
	v_mfma_f32_16x16x32_bf16 v[162:165], v[166:169], v[12:15], v[162:165]
	v_mfma_f32_16x16x32_bf16 v[166:169], v[170:173], v[32:35], 0
	s_waitcnt lgkmcnt(0)
	v_mfma_f32_16x16x32_bf16 v[170:173], v[174:177], v[0:3], 0
	ds_read_b128 v[174:177], v119 offset:64
	ds_read_b128 v[178:181], v119 offset:128
	s_waitcnt lgkmcnt(1)
	v_mfma_f32_16x16x32_bf16 v[166:169], v[174:177], v[102:105], v[166:169]
	ds_read_b128 v[174:177], v115 offset:17472
	ds_read_b128 v[182:185], v115 offset:17536
	s_waitcnt lgkmcnt(1)
	v_mfma_f32_16x16x32_bf16 v[170:173], v[174:177], v[4:7], v[170:173]
	v_mfma_f32_16x16x32_bf16 v[166:169], v[178:181], v[134:137], v[166:169]
	ds_read_b128 v[174:177], v119 offset:192
	ds_read_b128 v[178:181], v120
	s_waitcnt lgkmcnt(2)
	v_mfma_f32_16x16x32_bf16 v[170:173], v[182:185], v[8:11], v[170:173]
	s_waitcnt lgkmcnt(1)
	v_mfma_f32_16x16x32_bf16 v[166:169], v[174:177], v[146:149], v[166:169]
	ds_read_b128 v[174:177], v115 offset:17600
	ds_read_b128 v[182:185], v115 offset:21760
	s_waitcnt lgkmcnt(1)
	v_mfma_f32_16x16x32_bf16 v[170:173], v[174:177], v[12:15], v[170:173]
	v_mfma_f32_16x16x32_bf16 v[174:177], v[178:181], v[32:35], 0
	s_waitcnt lgkmcnt(0)
	v_mfma_f32_16x16x32_bf16 v[178:181], v[182:185], v[0:3], 0
	ds_read_b128 v[182:185], v120 offset:64
	ds_read_b128 v[186:189], v120 offset:128
	s_waitcnt lgkmcnt(1)
	v_mfma_f32_16x16x32_bf16 v[174:177], v[182:185], v[102:105], v[174:177]
	ds_read_b128 v[182:185], v115 offset:21824
	ds_read_b128 v[210:213], v115 offset:21888
	s_waitcnt lgkmcnt(1)
	v_mfma_f32_16x16x32_bf16 v[178:181], v[182:185], v[4:7], v[178:181]
	v_mfma_f32_16x16x32_bf16 v[174:177], v[186:189], v[134:137], v[174:177]
	ds_read_b128 v[182:185], v120 offset:192
	ds_read_b128 v[186:189], v121
	s_waitcnt lgkmcnt(2)
	v_mfma_f32_16x16x32_bf16 v[178:181], v[210:213], v[8:11], v[178:181]
	s_waitcnt lgkmcnt(1)
	v_mfma_f32_16x16x32_bf16 v[174:177], v[182:185], v[146:149], v[174:177]
	ds_read_b128 v[182:185], v115 offset:21952
	ds_read_b128 v[210:213], v115 offset:26112
	s_waitcnt lgkmcnt(1)
	v_mfma_f32_16x16x32_bf16 v[178:181], v[182:185], v[12:15], v[178:181]
	v_mfma_f32_16x16x32_bf16 v[182:185], v[186:189], v[32:35], 0
	ds_read_b128 v[186:189], v121 offset:64
	ds_read_b128 v[214:217], v115 offset:26176
	ds_read_b128 v[230:233], v121 offset:128
	s_waitcnt lgkmcnt(2)
	v_mfma_f32_16x16x32_bf16 v[182:185], v[186:189], v[102:105], v[182:185]
	ds_read_b32 v192, v100 offset:4096
	ds_read_b128 v[186:189], v115 offset:26240
	ds_read_b128 v[218:221], v122 offset:192
	s_waitcnt lgkmcnt(2)
	v_pk_fma_f32 v[36:37], v[192:193], v[126:127], v[36:37] op_sel_hi:[0,1,1]
	v_mfma_f32_16x16x32_bf16 v[210:213], v[210:213], v[0:3], 0
	v_fma_f32 v84, v190, v36, v84
	v_fma_f32 v85, v190, v37, v85
	v_pk_fma_f32 v[36:37], v[192:193], v[128:129], v[38:39] op_sel_hi:[0,1,1]
	v_pk_fma_f32 v[82:83], v[190:191], v[36:37], v[82:83] op_sel_hi:[0,1,1]
	ds_read_b128 v[36:39], v115 offset:26304
	v_mfma_f32_16x16x32_bf16 v[210:213], v[214:217], v[4:7], v[210:213]
	ds_read_b128 v[214:217], v121 offset:192
	v_pk_fma_f32 v[100:101], v[192:193], v[138:139], v[130:131] op_sel_hi:[0,1,1]
	v_pk_fma_f32 v[78:79], v[190:191], v[100:101], v[78:79] op_sel_hi:[0,1,1]
	s_waitcnt lgkmcnt(3)
	v_mfma_f32_16x16x32_bf16 v[126:129], v[186:189], v[8:11], v[210:213]
	ds_read_b128 v[186:189], v122
	v_pk_fma_f32 v[100:101], v[192:193], v[140:141], v[132:133] op_sel_hi:[0,1,1]
	ds_read_b128 v[130:133], v115 offset:30464
	s_waitcnt lgkmcnt(3)
	v_mfma_f32_16x16x32_bf16 v[36:39], v[36:39], v[12:15], v[126:129]
	v_fma_f32 v76, v190, v100, v76
	v_fma_f32 v77, v190, v101, v77
	v_pk_fma_f32 v[100:101], v[192:193], v[154:155], v[150:151] op_sel_hi:[0,1,1]
	ds_read_b128 v[138:141], v115 offset:30528
	ds_read_b128 v[126:129], v122 offset:64
	s_waitcnt lgkmcnt(3)
	v_mfma_f32_16x16x32_bf16 v[32:35], v[186:189], v[32:35], 0
	v_fma_f32 v72, v190, v100, v72
	v_fma_f32 v73, v190, v101, v73
	v_pk_fma_f32 v[100:101], v[192:193], v[156:157], v[152:153] op_sel_hi:[0,1,1]
	v_pk_fma_f32 v[70:71], v[190:191], v[100:101], v[70:71] op_sel_hi:[0,1,1]
	v_pk_fma_f32 v[100:101], v[192:193], v[162:163], v[158:159] op_sel_hi:[0,1,1]
	v_pk_fma_f32 v[64:65], v[190:191], v[100:101], v[64:65] op_sel_hi:[0,1,1]
	v_pk_fma_f32 v[100:101], v[192:193], v[164:165], v[160:161] op_sel_hi:[0,1,1]
	ds_read_b128 v[150:153], v122 offset:128
	s_waitcnt lgkmcnt(1)
	v_mfma_f32_16x16x32_bf16 v[32:35], v[126:129], v[102:105], v[32:35]
	v_fma_f32 v62, v190, v100, v62
	v_fma_f32 v63, v190, v101, v63
	ds_read_b128 v[100:103], v115 offset:30592
	v_pk_fma_f32 v[126:127], v[192:193], v[170:171], v[166:167] op_sel_hi:[0,1,1]
	v_mfma_f32_16x16x32_bf16 v[130:133], v[130:133], v[0:3], 0
	v_fma_f32 v58, v190, v126, v58
	v_fma_f32 v59, v190, v127, v59
	v_pk_fma_f32 v[126:127], v[192:193], v[172:173], v[168:169] op_sel_hi:[0,1,1]
	v_pk_fma_f32 v[56:57], v[190:191], v[126:127], v[56:57] op_sel_hi:[0,1,1]
	v_mfma_f32_16x16x32_bf16 v[182:185], v[230:233], v[134:137], v[182:185]
	v_fma_f32 v126, v192, v178, v174
	v_fma_f32 v127, v192, v179, v175
	v_pk_fma_f32 v[52:53], v[190:191], v[126:127], v[52:53] op_sel_hi:[0,1,1]
	s_waitcnt lgkmcnt(0)
	v_mfma_f32_16x16x32_bf16 v[104:107], v[138:141], v[4:7], v[130:133]
	s_barrier
	v_mfma_f32_16x16x32_bf16 v[182:185], v[214:217], v[146:149], v[182:185]
	v_mfma_f32_16x16x32_bf16 v[32:35], v[150:153], v[134:137], v[32:35]
	v_mfma_f32_16x16x32_bf16 v[100:103], v[100:103], v[8:11], v[104:107]
	s_nop 5
	v_fma_f32 v36, v192, v36, v182
	v_fma_f32 v37, v192, v37, v183
	v_pk_fma_f32 v[46:47], v[190:191], v[36:37], v[46:47] op_sel_hi:[0,1,1]
	v_pk_fma_f32 v[36:37], v[192:193], v[38:39], v[184:185] op_sel_hi:[0,1,1]
	v_mfma_f32_16x16x32_bf16 v[32:35], v[218:221], v[146:149], v[32:35]
	v_fma_f32 v44, v190, v36, v44
	v_fma_f32 v45, v190, v37, v45
	v_pk_fma_f32 v[104:105], v[192:193], v[180:181], v[176:177] op_sel_hi:[0,1,1]
	v_pk_fma_f32 v[50:51], v[190:191], v[104:105], v[50:51] op_sel_hi:[0,1,1]
	v_mfma_f32_16x16x32_bf16 v[36:39], v[142:145], v[12:15], v[100:103]
	s_nop 7
	v_pk_fma_f32 v[32:33], v[192:193], v[36:37], v[32:33] op_sel_hi:[0,1,1]
	v_pk_fma_f32 v[42:43], v[190:191], v[32:33], v[42:43] op_sel_hi:[0,1,1]
	v_pk_fma_f32 v[32:33], v[192:193], v[38:39], v[34:35] op_sel_hi:[0,1,1]
	v_pk_fma_f32 v[40:41], v[190:191], v[32:33], v[40:41] op_sel_hi:[0,1,1]
	s_cbranch_vccnz .LBB0_810
	s_mov_b64 s[70:71], 0
	s_waitcnt vmcnt(3)
	ds_write_b128 v202, v[28:31]
	s_waitcnt vmcnt(2)
	ds_write_b128 v204, v[24:27]
	s_waitcnt vmcnt(1)
	ds_write_b128 v206, v[20:23]
	s_waitcnt vmcnt(0)
	ds_write_b128 v208, v[16:19]
